# v36 + row-panel exchange polls with s_sleep 1 instead of s_sleep 2 in the two fused-norm GEMM epilogues
# baseline (speedup 1.0000x reference)
.LBB0_700:
	s_or_b64 exec, exec, s[76:77]
	v_cndmask_b32_e64 v182, 0, 1, s[0:1]
	v_cmp_ne_u32_e32 vcc, 0, v182
	s_cbranch_vccz .LBB0_696
	s_memrealtime s[0:1]
	s_waitcnt lgkmcnt(0)
	s_sub_u32 s0, s0, s62
	s_subb_u32 s1, s1, s63
	v_cmp_lt_u64_e32 vcc, s[0:1], v[200:201]
	s_mov_b64 s[0:1], -1
	s_cbranch_vccz .LBB0_697
	s_sleep 1
	s_mov_b64 s[0:1], 0
	s_branch .LBB0_697

.LBB0_706:
	global_load_dwordx2 v[212:213], v[210:211], off sc1
	global_load_dwordx2 v[214:215], v[210:211], off offset:8 sc1
	global_load_dwordx2 v[216:217], v[210:211], off offset:16 sc1
	global_load_dwordx2 v[218:219], v[210:211], off offset:24 sc1
	s_waitcnt vmcnt(3)
	v_cmp_eq_u32_e32 vcc, 0, v212
	v_cmp_gt_u64_e64 s[0:1], s[40:41], v[212:213]
	s_waitcnt vmcnt(2)
	v_cmp_eq_u32_e64 s[16:17], 0, v214
	v_cmp_gt_u64_e64 s[18:19], s[40:41], v[214:215]
	s_waitcnt vmcnt(1)
	v_cmp_eq_u32_e64 s[20:21], 0, v216
	v_cmp_gt_u64_e64 s[22:23], s[40:41], v[216:217]
	s_or_b64 s[0:1], s[0:1], vcc
	s_or_b64 s[16:17], s[18:19], s[16:17]
	s_waitcnt vmcnt(0)
	v_cmp_eq_u32_e64 s[24:25], 0, v218
	v_cmp_gt_u64_e64 s[26:27], s[40:41], v[218:219]
	s_or_b64 s[18:19], s[22:23], s[20:21]
	s_or_b64 s[0:1], s[0:1], s[16:17]
	s_or_b64 s[0:1], s[0:1], s[18:19]
	s_or_b64 s[16:17], s[26:27], s[24:25]
	s_or_b64 vcc, s[0:1], s[16:17]
	s_cbranch_vccz .LBB0_704
	s_memrealtime s[16:17]
	s_mov_b64 s[0:1], -1
	s_waitcnt lgkmcnt(0)
	s_sub_u32 s16, s16, s62
	s_subb_u32 s17, s17, s63
	v_cmp_lt_u64_e32 vcc, s[16:17], v[200:201]
	s_mov_b64 s[16:17], -1
	s_cbranch_vccz .LBB0_709
	s_sleep 1
	s_cbranch_execnz .LBB0_705
	s_branch .LBB0_710

.LBB0_1068:
	s_or_b64 exec, exec, s[44:45]
	v_cndmask_b32_e64 v148, 0, 1, s[8:9]
	v_cmp_ne_u32_e32 vcc, 0, v148
	s_cbranch_vccz .LBB0_1064
	s_memrealtime s[8:9]
	s_waitcnt lgkmcnt(0)
	s_sub_u32 s8, s8, s42
	s_subb_u32 s9, s9, s43
	v_cmp_lt_u64_e32 vcc, s[8:9], v[170:171]
	s_mov_b64 s[8:9], -1
	s_cbranch_vccz .LBB0_1065
	s_sleep 1
	s_mov_b64 s[8:9], 0
	s_branch .LBB0_1065

.LBB0_1074:
	global_load_dwordx2 v[148:149], v[146:147], off sc1
	global_load_dwordx2 v[176:177], v[146:147], off offset:8 sc1
	global_load_dwordx2 v[178:179], v[146:147], off offset:16 sc1
	global_load_dwordx2 v[180:181], v[146:147], off offset:24 sc1
	s_waitcnt vmcnt(3)
	v_cmp_eq_u32_e32 vcc, 0, v148
	v_cmp_gt_u64_e64 s[8:9], s[26:27], v[148:149]
	s_waitcnt vmcnt(2)
	v_cmp_eq_u32_e64 s[10:11], 0, v176
	v_cmp_gt_u64_e64 s[12:13], s[26:27], v[176:177]
	s_waitcnt vmcnt(1)
	v_cmp_eq_u32_e64 s[14:15], 0, v178
	v_cmp_gt_u64_e64 s[16:17], s[26:27], v[178:179]
	s_or_b64 s[8:9], s[8:9], vcc
	s_or_b64 s[10:11], s[12:13], s[10:11]
	s_waitcnt vmcnt(0)
	v_cmp_eq_u32_e64 s[18:19], 0, v180
	v_cmp_gt_u64_e64 s[20:21], s[26:27], v[180:181]
	s_or_b64 s[12:13], s[16:17], s[14:15]
	s_or_b64 s[8:9], s[8:9], s[10:11]
	s_or_b64 s[8:9], s[8:9], s[12:13]
	s_or_b64 s[10:11], s[20:21], s[18:19]
	s_or_b64 vcc, s[8:9], s[10:11]
	s_cbranch_vccz .LBB0_1072
	s_memrealtime s[10:11]
	s_mov_b64 s[8:9], -1
	s_waitcnt lgkmcnt(0)
	s_sub_u32 s10, s10, s42
	s_subb_u32 s11, s11, s43
	v_cmp_lt_u64_e32 vcc, s[10:11], v[170:171]
	s_mov_b64 s[10:11], -1
	s_cbranch_vccz .LBB0_1077
	s_sleep 1
	s_cbranch_execnz .LBB0_1073
	s_branch .LBB0_1078
